# v46 plus down-GEMM epilogue first pass residual loads streamed through a 5-deep register ring with counted waits
# speedup vs baseline: 1.0003x; 1.0003x over previous
.LBB0_1330:
	v_lshl_add_u32 v152, s76, 8, v200
	v_ashrrev_i32_e32 v153, 31, v152
	v_lshl_or_b32 v142, s77, 8, v204
	v_lshlrev_b64 v[140:141], 13, v[152:153]
	v_ashrrev_i32_e32 v143, 31, v142
	v_lshl_add_u64 v[140:141], s[54:55], 0, v[140:141]
	v_lshl_add_u64 v[140:141], v[142:143], 2, v[140:141]
	v_mov_b32_e32 v246, v140
	v_mov_b32_e32 v247, v141
	global_load_dwordx4 v[206:209], v[246:247], off
	global_load_dwordx4 v[210:213], v[246:247], off offset:16
	global_load_dwordx4 v[214:217], v[246:247], off offset:512
	global_load_dwordx4 v[218:221], v[246:247], off offset:528
	s_mov_b32 s98, 0x20000
	s_mov_b32 s99, 0
	v_lshl_add_u64 v[246:247], v[246:247], 0, s[98:99]
	global_load_dwordx4 v[222:225], v[246:247], off
	global_load_dwordx4 v[226:229], v[246:247], off offset:16
	global_load_dwordx4 v[230:233], v[246:247], off offset:512
	global_load_dwordx4 v[234:237], v[246:247], off offset:528
	s_mov_b32 s98, 0x20000
	s_mov_b32 s99, 0
	v_lshl_add_u64 v[246:247], v[246:247], 0, s[98:99]
	global_load_dwordx4 v[238:241], v[246:247], off
	global_load_dwordx4 v[242:245], v[246:247], off offset:16
	s_waitcnt vmcnt(8)
	v_mov_b32_e32 v144, v210
	v_mov_b32_e32 v145, v211
	v_mov_b32_e32 v146, v212
	v_mov_b32_e32 v147, v213
	v_mov_b32_e32 v148, v206
	v_mov_b32_e32 v149, v207
	v_mov_b32_e32 v150, v208
	v_mov_b32_e32 v151, v209
	global_load_dwordx4 v[206:209], v[246:247], off offset:512
	global_load_dwordx4 v[210:213], v[246:247], off offset:528
	v_pk_add_f32 v[124:125], v[124:125], v[146:147]
	v_pk_add_f32 v[126:127], v[126:127], v[148:149]
	v_pk_add_f32 v[128:129], v[128:129], v[150:151]
	v_pk_add_f32 v[122:123], v[122:123], v[144:145]
	v_mul_f32_e32 v144, v127, v127
	v_mul_f32_e32 v145, v129, v129
	v_fmac_f32_e32 v144, v126, v126
	v_fmac_f32_e32 v145, v128, v128
	v_add_f32_e32 v144, v144, v145
	v_mul_f32_e32 v145, v123, v123
	v_fmac_f32_e32 v145, v122, v122
	v_add_f32_e32 v144, v144, v145
	v_mul_f32_e32 v145, v125, v125
	v_fmac_f32_e32 v145, v124, v124
	v_add_f32_e32 v150, v145, v144
	s_waitcnt vmcnt(8)
	v_mov_b32_e32 v146, v218
	v_mov_b32_e32 v147, v219
	v_mov_b32_e32 v148, v220
	v_mov_b32_e32 v149, v221
	v_mov_b32_e32 v154, v214
	v_mov_b32_e32 v155, v215
	v_mov_b32_e32 v156, v216
	v_mov_b32_e32 v157, v217
	s_mov_b32 s98, 0x20000
	s_mov_b32 s99, 0
	v_lshl_add_u64 v[246:247], v[246:247], 0, s[98:99]
	global_load_dwordx4 v[214:217], v[246:247], off
	global_load_dwordx4 v[218:221], v[246:247], off offset:16
	v_pk_add_f32 v[116:117], v[116:117], v[148:149]
	v_pk_add_f32 v[120:121], v[120:121], v[156:157]
	v_pk_add_f32 v[144:145], v[118:119], v[154:155]
	v_pk_add_f32 v[118:119], v[114:115], v[146:147]
	v_mul_f32_e32 v114, v145, v145
	v_mul_f32_e32 v115, v121, v121
	v_fmac_f32_e32 v114, v144, v144
	v_fmac_f32_e32 v115, v120, v120
	v_add_f32_e32 v114, v114, v115
	v_mul_f32_e32 v115, v119, v119
	v_fmac_f32_e32 v115, v118, v118
	v_add_f32_e32 v114, v114, v115
	v_mul_f32_e32 v115, v117, v117
	v_fmac_f32_e32 v115, v116, v116
	v_add_f32_e32 v114, v115, v114
	v_add_f32_e32 v114, v150, v114
	ds_bpermute_b32 v115, v202, v114
	s_waitcnt lgkmcnt(0)
	v_add_f32_e32 v146, v114, v115
	ds_bpermute_b32 v147, v203, v146
	v_lshl_add_u64 v[114:115], v[152:153], 2, s[14:15]
	s_and_saveexec_b64 s[18:19], s[0:1]
	s_cbranch_execz .LBB0_1332
	s_waitcnt lgkmcnt(0)
	v_add_f32_e32 v146, v146, v147
	flat_atomic_add_f32 v[114:115], v146
.LBB0_1332:
	s_or_b64 exec, exec, s[18:19]
	v_or_b32_e32 v168, 16, v152
	v_ashrrev_i32_e32 v169, 31, v168
	s_waitcnt lgkmcnt(0)
	v_lshlrev_b64 v[146:147], 13, v[168:169]
	v_lshl_add_u64 v[146:147], s[54:55], 0, v[146:147]
	v_lshl_add_u64 v[146:147], v[142:143], 2, v[146:147]
	s_waitcnt vmcnt(8)
	v_mov_b32_e32 v148, v226
	v_mov_b32_e32 v149, v227
	v_mov_b32_e32 v150, v228
	v_mov_b32_e32 v151, v229
	v_mov_b32_e32 v154, v222
	v_mov_b32_e32 v155, v223
	v_mov_b32_e32 v156, v224
	v_mov_b32_e32 v157, v225
	global_load_dwordx4 v[222:225], v[246:247], off offset:512
	global_load_dwordx4 v[226:229], v[246:247], off offset:528
	v_pk_add_f32 v[106:107], v[106:107], v[148:149]
	v_pk_add_f32 v[112:113], v[112:113], v[156:157]
	v_pk_add_f32 v[110:111], v[110:111], v[154:155]
	v_mul_f32_e32 v149, v113, v113
	v_mul_f32_e32 v148, v111, v111
	v_fmac_f32_e32 v148, v110, v110
	v_fmac_f32_e32 v149, v112, v112
	v_add_f32_e32 v148, v148, v149
	v_mul_f32_e32 v149, v107, v107
	v_pk_add_f32 v[108:109], v[108:109], v[150:151]
	v_fmac_f32_e32 v149, v106, v106
	v_add_f32_e32 v148, v148, v149
	v_mul_f32_e32 v149, v109, v109
	v_fmac_f32_e32 v149, v108, v108
	v_add_f32_e32 v153, v149, v148
	s_waitcnt vmcnt(8)
	v_mov_b32_e32 v148, v234
	v_mov_b32_e32 v149, v235
	v_mov_b32_e32 v150, v236
	v_mov_b32_e32 v151, v237
	v_mov_b32_e32 v154, v230
	v_mov_b32_e32 v155, v231
	v_mov_b32_e32 v156, v232
	v_mov_b32_e32 v157, v233
	s_mov_b32 s98, 0xa0000
	s_mov_b32 s99, 0
	v_lshl_add_u64 v[246:247], v[246:247], 0, s[98:99]
	global_load_dwordx4 v[230:233], v[246:247], off
	global_load_dwordx4 v[234:237], v[246:247], off offset:16
	v_pk_add_f32 v[98:99], v[98:99], v[148:149]
	v_pk_add_f32 v[104:105], v[104:105], v[156:157]
	v_pk_add_f32 v[102:103], v[102:103], v[154:155]
	v_mul_f32_e32 v149, v105, v105
	v_mul_f32_e32 v148, v103, v103
	v_fmac_f32_e32 v148, v102, v102
	v_fmac_f32_e32 v149, v104, v104
	v_add_f32_e32 v148, v148, v149
	v_mul_f32_e32 v149, v99, v99
	v_pk_add_f32 v[100:101], v[100:101], v[150:151]
	v_fmac_f32_e32 v149, v98, v98
	v_add_f32_e32 v148, v148, v149
	v_mul_f32_e32 v149, v101, v101
	v_fmac_f32_e32 v149, v100, v100
	v_add_f32_e32 v148, v149, v148
	v_add_f32_e32 v148, v153, v148
	ds_bpermute_b32 v149, v202, v148
	v_lshl_add_u64 v[150:151], v[168:169], 2, s[14:15]
	s_waitcnt lgkmcnt(0)
	v_add_f32_e32 v148, v148, v149
	ds_bpermute_b32 v149, v203, v148
	s_and_saveexec_b64 s[18:19], s[0:1]
	s_cbranch_execz .LBB0_1334
	s_waitcnt lgkmcnt(0)
	v_add_f32_e32 v148, v148, v149
	flat_atomic_add_f32 v[150:151], v148
.LBB0_1334:
	s_or_b64 exec, exec, s[18:19]
	v_or_b32_e32 v172, 32, v152
	v_ashrrev_i32_e32 v173, 31, v172
	s_waitcnt lgkmcnt(0)
	v_lshlrev_b64 v[148:149], 13, v[172:173]
	v_lshl_add_u64 v[148:149], s[54:55], 0, v[148:149]
	v_lshl_add_u64 v[148:149], v[142:143], 2, v[148:149]
	s_waitcnt vmcnt(8)
	v_mov_b32_e32 v154, v242
	v_mov_b32_e32 v155, v243
	v_mov_b32_e32 v156, v244
	v_mov_b32_e32 v157, v245
	v_mov_b32_e32 v168, v238
	v_mov_b32_e32 v169, v239
	v_mov_b32_e32 v170, v240
	v_mov_b32_e32 v171, v241
	global_load_dwordx4 v[238:241], v[246:247], off offset:512
	global_load_dwordx4 v[242:245], v[246:247], off offset:528
	v_pk_add_f32 v[88:89], v[88:89], v[154:155]
	v_pk_add_f32 v[94:95], v[94:95], v[170:171]
	v_pk_add_f32 v[92:93], v[92:93], v[168:169]
	v_mul_f32_e32 v154, v95, v95
	v_mul_f32_e32 v153, v93, v93
	v_fmac_f32_e32 v153, v92, v92
	v_fmac_f32_e32 v154, v94, v94
	v_add_f32_e32 v153, v153, v154
	v_mul_f32_e32 v154, v89, v89
	v_pk_add_f32 v[90:91], v[90:91], v[156:157]
	v_fmac_f32_e32 v154, v88, v88
	v_add_f32_e32 v153, v153, v154
	v_mul_f32_e32 v154, v91, v91
	v_fmac_f32_e32 v154, v90, v90
	v_add_f32_e32 v153, v154, v153
	s_waitcnt vmcnt(8)
	v_mov_b32_e32 v154, v210
	v_mov_b32_e32 v155, v211
	v_mov_b32_e32 v156, v212
	v_mov_b32_e32 v157, v213
	v_mov_b32_e32 v168, v206
	v_mov_b32_e32 v169, v207
	v_mov_b32_e32 v170, v208
	v_mov_b32_e32 v171, v209
	s_mov_b32 s98, 0x20000
	s_mov_b32 s99, 0
	v_lshl_add_u64 v[246:247], v[246:247], 0, s[98:99]
	global_load_dwordx4 v[206:209], v[246:247], off
	global_load_dwordx4 v[210:213], v[246:247], off offset:16
	v_pk_add_f32 v[80:81], v[80:81], v[154:155]
	v_pk_add_f32 v[86:87], v[86:87], v[170:171]
	v_pk_add_f32 v[84:85], v[84:85], v[168:169]
	v_mul_f32_e32 v155, v87, v87
	v_mul_f32_e32 v154, v85, v85
	v_fmac_f32_e32 v154, v84, v84
	v_fmac_f32_e32 v155, v86, v86
	v_add_f32_e32 v154, v154, v155
	v_mul_f32_e32 v155, v81, v81
	v_pk_add_f32 v[82:83], v[82:83], v[156:157]
	v_fmac_f32_e32 v155, v80, v80
	v_add_f32_e32 v154, v154, v155
	v_mul_f32_e32 v155, v83, v83
	v_fmac_f32_e32 v155, v82, v82
	v_add_f32_e32 v154, v155, v154
	v_add_f32_e32 v153, v153, v154
	ds_bpermute_b32 v154, v202, v153
	v_lshl_add_u64 v[156:157], v[172:173], 2, s[14:15]
	s_waitcnt lgkmcnt(0)
	v_add_f32_e32 v153, v153, v154
	ds_bpermute_b32 v154, v203, v153
	s_and_saveexec_b64 s[18:19], s[0:1]
	v_readlane_b32 s86, v255, 44
	s_mov_b64 s[84:85], s[88:89]
	s_mov_b32 s83, s94
	v_readlane_b32 s87, v255, 45
	s_cbranch_execz .LBB0_1336
	s_waitcnt lgkmcnt(0)
	v_add_f32_e32 v153, v153, v154
	flat_atomic_add_f32 v[156:157], v153
.LBB0_1336:
	s_or_b64 exec, exec, s[18:19]
	v_or_b32_e32 v176, 48, v152
	v_ashrrev_i32_e32 v177, 31, v176
	s_waitcnt lgkmcnt(0)
	v_lshlrev_b64 v[154:155], 13, v[176:177]
	v_lshl_add_u64 v[154:155], s[54:55], 0, v[154:155]
	v_lshl_add_u64 v[154:155], v[142:143], 2, v[154:155]
	s_waitcnt vmcnt(8)
	v_mov_b32_e32 v168, v218
	v_mov_b32_e32 v169, v219
	v_mov_b32_e32 v170, v220
	v_mov_b32_e32 v171, v221
	v_mov_b32_e32 v172, v214
	v_mov_b32_e32 v173, v215
	v_mov_b32_e32 v174, v216
	v_mov_b32_e32 v175, v217
	global_load_dwordx4 v[214:217], v[246:247], off offset:512
	global_load_dwordx4 v[218:221], v[246:247], off offset:528
	v_pk_add_f32 v[72:73], v[72:73], v[168:169]
	v_pk_add_f32 v[78:79], v[78:79], v[174:175]
	v_pk_add_f32 v[76:77], v[76:77], v[172:173]
	v_mul_f32_e32 v168, v79, v79
	v_mul_f32_e32 v153, v77, v77
	v_fmac_f32_e32 v153, v76, v76
	v_fmac_f32_e32 v168, v78, v78
	v_add_f32_e32 v153, v153, v168
	v_mul_f32_e32 v168, v73, v73
	v_pk_add_f32 v[74:75], v[74:75], v[170:171]
	v_fmac_f32_e32 v168, v72, v72
	v_add_f32_e32 v153, v153, v168
	v_mul_f32_e32 v168, v75, v75
	v_fmac_f32_e32 v168, v74, v74
	v_add_f32_e32 v153, v168, v153
	s_waitcnt vmcnt(8)
	v_mov_b32_e32 v168, v226
	v_mov_b32_e32 v169, v227
	v_mov_b32_e32 v170, v228
	v_mov_b32_e32 v171, v229
	v_mov_b32_e32 v172, v222
	v_mov_b32_e32 v173, v223
	v_mov_b32_e32 v174, v224
	v_mov_b32_e32 v175, v225
	s_mov_b32 s98, 0x20000
	s_mov_b32 s99, 0
	v_lshl_add_u64 v[246:247], v[246:247], 0, s[98:99]
	global_load_dwordx4 v[222:225], v[246:247], off
	global_load_dwordx4 v[226:229], v[246:247], off offset:16
	v_pk_add_f32 v[64:65], v[64:65], v[168:169]
	v_pk_add_f32 v[70:71], v[70:71], v[174:175]
	v_pk_add_f32 v[68:69], v[68:69], v[172:173]
	v_mul_f32_e32 v169, v71, v71
	v_mul_f32_e32 v168, v69, v69
	v_fmac_f32_e32 v168, v68, v68
	v_fmac_f32_e32 v169, v70, v70
	v_add_f32_e32 v168, v168, v169
	v_mul_f32_e32 v169, v65, v65
	v_pk_add_f32 v[66:67], v[66:67], v[170:171]
	v_fmac_f32_e32 v169, v64, v64
	v_add_f32_e32 v168, v168, v169
	v_mul_f32_e32 v169, v67, v67
	v_fmac_f32_e32 v169, v66, v66
	v_add_f32_e32 v168, v169, v168
	v_add_f32_e32 v153, v153, v168
	ds_bpermute_b32 v168, v202, v153
	v_lshl_add_u64 v[170:171], v[176:177], 2, s[14:15]
	s_waitcnt lgkmcnt(0)
	v_add_f32_e32 v153, v153, v168
	ds_bpermute_b32 v168, v203, v153
	s_and_saveexec_b64 s[18:19], s[0:1]
	s_cbranch_execz .LBB0_1338
	s_waitcnt lgkmcnt(0)
	v_add_f32_e32 v153, v153, v168
	flat_atomic_add_f32 v[170:171], v153
.LBB0_1338:
	s_or_b64 exec, exec, s[18:19]
	v_add_u32_e32 v172, 0x80, v152
	v_ashrrev_i32_e32 v173, 31, v172
	s_waitcnt lgkmcnt(0)
	v_lshlrev_b64 v[168:169], 13, v[172:173]
	v_lshl_add_u64 v[168:169], s[54:55], 0, v[168:169]
	v_lshl_add_u64 v[168:169], v[142:143], 2, v[168:169]
	s_waitcnt vmcnt(8)
	v_mov_b32_e32 v174, v234
	v_mov_b32_e32 v175, v235
	v_mov_b32_e32 v176, v236
	v_mov_b32_e32 v177, v237
	v_mov_b32_e32 v178, v230
	v_mov_b32_e32 v179, v231
	v_mov_b32_e32 v180, v232
	v_mov_b32_e32 v181, v233
	global_load_dwordx4 v[230:233], v[246:247], off offset:512
	global_load_dwordx4 v[234:237], v[246:247], off offset:528
	v_pk_add_f32 v[56:57], v[56:57], v[174:175]
	v_pk_add_f32 v[62:63], v[62:63], v[180:181]
	v_pk_add_f32 v[60:61], v[60:61], v[178:179]
	v_mul_f32_e32 v174, v63, v63
	v_mul_f32_e32 v153, v61, v61
	v_fmac_f32_e32 v153, v60, v60
	v_fmac_f32_e32 v174, v62, v62
	v_add_f32_e32 v153, v153, v174
	v_mul_f32_e32 v174, v57, v57
	v_pk_add_f32 v[58:59], v[58:59], v[176:177]
	v_fmac_f32_e32 v174, v56, v56
	v_add_f32_e32 v153, v153, v174
	v_mul_f32_e32 v174, v59, v59
	v_fmac_f32_e32 v174, v58, v58
	v_add_f32_e32 v153, v174, v153
	s_waitcnt vmcnt(8)
	v_mov_b32_e32 v174, v242
	v_mov_b32_e32 v175, v243
	v_mov_b32_e32 v176, v244
	v_mov_b32_e32 v177, v245
	v_mov_b32_e32 v178, v238
	v_mov_b32_e32 v179, v239
	v_mov_b32_e32 v180, v240
	v_mov_b32_e32 v181, v241
	s_mov_b32 s98, 0x20000
	s_mov_b32 s99, 0
	v_lshl_add_u64 v[246:247], v[246:247], 0, s[98:99]
	global_load_dwordx4 v[238:241], v[246:247], off
	global_load_dwordx4 v[242:245], v[246:247], off offset:16
	v_pk_add_f32 v[48:49], v[48:49], v[174:175]
	v_pk_add_f32 v[54:55], v[54:55], v[180:181]
	v_pk_add_f32 v[52:53], v[52:53], v[178:179]
	v_mul_f32_e32 v175, v55, v55
	v_mul_f32_e32 v174, v53, v53
	v_fmac_f32_e32 v174, v52, v52
	v_fmac_f32_e32 v175, v54, v54
	v_add_f32_e32 v174, v174, v175
	v_mul_f32_e32 v175, v49, v49
	v_pk_add_f32 v[50:51], v[50:51], v[176:177]
	v_fmac_f32_e32 v175, v48, v48
	v_add_f32_e32 v174, v174, v175
	v_mul_f32_e32 v175, v51, v51
	v_fmac_f32_e32 v175, v50, v50
	v_add_f32_e32 v174, v175, v174
	v_add_f32_e32 v153, v153, v174
	ds_bpermute_b32 v174, v202, v153
	s_waitcnt lgkmcnt(0)
	v_add_f32_e32 v153, v153, v174
	ds_bpermute_b32 v174, v203, v153
	s_and_saveexec_b64 s[18:19], s[0:1]
	s_cbranch_execz .LBB0_1340
	v_lshl_add_u64 v[172:173], v[172:173], 2, s[14:15]
	s_waitcnt lgkmcnt(0)
	v_add_f32_e32 v153, v153, v174
	flat_atomic_add_f32 v[172:173], v153
.LBB0_1340:
	s_or_b64 exec, exec, s[18:19]
	s_waitcnt lgkmcnt(0)
	v_add_u32_e32 v174, 0x90, v152
	v_ashrrev_i32_e32 v175, 31, v174
	v_lshlrev_b64 v[172:173], 13, v[174:175]
	v_lshl_add_u64 v[172:173], s[54:55], 0, v[172:173]
	v_lshl_add_u64 v[172:173], v[142:143], 2, v[172:173]
	s_waitcnt vmcnt(8)
	v_mov_b32_e32 v176, v210
	v_mov_b32_e32 v177, v211
	v_mov_b32_e32 v178, v212
	v_mov_b32_e32 v179, v213
	v_mov_b32_e32 v180, v206
	v_mov_b32_e32 v181, v207
	v_mov_b32_e32 v182, v208
	v_mov_b32_e32 v183, v209
	global_load_dwordx4 v[206:209], v[246:247], off offset:512
	global_load_dwordx4 v[210:213], v[246:247], off offset:528
	v_pk_add_f32 v[40:41], v[40:41], v[176:177]
	v_pk_add_f32 v[46:47], v[46:47], v[182:183]
	v_pk_add_f32 v[44:45], v[44:45], v[180:181]
	v_mul_f32_e32 v176, v47, v47
	v_mul_f32_e32 v153, v45, v45
	v_fmac_f32_e32 v153, v44, v44
	v_fmac_f32_e32 v176, v46, v46
	v_add_f32_e32 v153, v153, v176
	v_mul_f32_e32 v176, v41, v41
	v_pk_add_f32 v[42:43], v[42:43], v[178:179]
	v_fmac_f32_e32 v176, v40, v40
	v_add_f32_e32 v153, v153, v176
	v_mul_f32_e32 v176, v43, v43
	v_fmac_f32_e32 v176, v42, v42
	v_add_f32_e32 v153, v176, v153
	s_waitcnt vmcnt(8)
	v_mov_b32_e32 v176, v218
	v_mov_b32_e32 v177, v219
	v_mov_b32_e32 v178, v220
	v_mov_b32_e32 v179, v221
	v_mov_b32_e32 v180, v214
	v_mov_b32_e32 v181, v215
	v_mov_b32_e32 v182, v216
	v_mov_b32_e32 v183, v217
	v_pk_add_f32 v[32:33], v[32:33], v[176:177]
	v_pk_add_f32 v[38:39], v[38:39], v[182:183]
	v_pk_add_f32 v[36:37], v[36:37], v[180:181]
	v_mul_f32_e32 v177, v39, v39
	v_mul_f32_e32 v176, v37, v37
	v_fmac_f32_e32 v176, v36, v36
	v_fmac_f32_e32 v177, v38, v38
	v_add_f32_e32 v176, v176, v177
	v_mul_f32_e32 v177, v33, v33
	v_pk_add_f32 v[34:35], v[34:35], v[178:179]
	v_fmac_f32_e32 v177, v32, v32
	v_add_f32_e32 v176, v176, v177
	v_mul_f32_e32 v177, v35, v35
	v_fmac_f32_e32 v177, v34, v34
	v_add_f32_e32 v176, v177, v176
	v_add_f32_e32 v153, v153, v176
	ds_bpermute_b32 v176, v202, v153
	s_waitcnt lgkmcnt(0)
	v_add_f32_e32 v153, v153, v176
	ds_bpermute_b32 v176, v203, v153
	s_and_saveexec_b64 s[18:19], s[0:1]
	s_cbranch_execz .LBB0_1342
	v_lshl_add_u64 v[174:175], v[174:175], 2, s[14:15]
	s_waitcnt lgkmcnt(0)
	v_add_f32_e32 v153, v153, v176
	flat_atomic_add_f32 v[174:175], v153
.LBB0_1342:
	s_or_b64 exec, exec, s[18:19]
	s_waitcnt lgkmcnt(0)
	v_add_u32_e32 v176, 0xa0, v152
	v_ashrrev_i32_e32 v177, 31, v176
	v_lshlrev_b64 v[174:175], 13, v[176:177]
	v_lshl_add_u64 v[174:175], s[54:55], 0, v[174:175]
	v_lshl_add_u64 v[174:175], v[142:143], 2, v[174:175]
	s_waitcnt vmcnt(6)
	v_mov_b32_e32 v178, v226
	v_mov_b32_e32 v179, v227
	v_mov_b32_e32 v180, v228
	v_mov_b32_e32 v181, v229
	v_mov_b32_e32 v182, v222
	v_mov_b32_e32 v183, v223
	v_mov_b32_e32 v184, v224
	v_mov_b32_e32 v185, v225
	v_pk_add_f32 v[24:25], v[24:25], v[178:179]
	v_pk_add_f32 v[30:31], v[30:31], v[184:185]
	v_pk_add_f32 v[28:29], v[28:29], v[182:183]
	v_mul_f32_e32 v178, v31, v31
	v_mul_f32_e32 v153, v29, v29
	v_fmac_f32_e32 v153, v28, v28
	v_fmac_f32_e32 v178, v30, v30
	v_add_f32_e32 v153, v153, v178
	v_mul_f32_e32 v178, v25, v25
	v_pk_add_f32 v[26:27], v[26:27], v[180:181]
	v_fmac_f32_e32 v178, v24, v24
	v_add_f32_e32 v153, v153, v178
	v_mul_f32_e32 v178, v27, v27
	v_fmac_f32_e32 v178, v26, v26
	v_add_f32_e32 v153, v178, v153
	s_waitcnt vmcnt(4)
	v_mov_b32_e32 v178, v234
	v_mov_b32_e32 v179, v235
	v_mov_b32_e32 v180, v236
	v_mov_b32_e32 v181, v237
	v_mov_b32_e32 v182, v230
	v_mov_b32_e32 v183, v231
	v_mov_b32_e32 v184, v232
	v_mov_b32_e32 v185, v233
	v_pk_add_f32 v[16:17], v[16:17], v[178:179]
	v_pk_add_f32 v[22:23], v[22:23], v[184:185]
	v_pk_add_f32 v[20:21], v[20:21], v[182:183]
	v_mul_f32_e32 v179, v23, v23
	v_mul_f32_e32 v178, v21, v21
	v_fmac_f32_e32 v178, v20, v20
	v_fmac_f32_e32 v179, v22, v22
	v_add_f32_e32 v178, v178, v179
	v_mul_f32_e32 v179, v17, v17
	v_pk_add_f32 v[18:19], v[18:19], v[180:181]
	v_fmac_f32_e32 v179, v16, v16
	v_add_f32_e32 v178, v178, v179
	v_mul_f32_e32 v179, v19, v19
	v_fmac_f32_e32 v179, v18, v18
	v_add_f32_e32 v178, v179, v178
	v_add_f32_e32 v153, v153, v178
	ds_bpermute_b32 v178, v202, v153
	s_waitcnt lgkmcnt(0)
	v_add_f32_e32 v153, v153, v178
	ds_bpermute_b32 v178, v203, v153
	s_and_saveexec_b64 s[18:19], s[0:1]
	s_cbranch_execz .LBB0_1344
	v_lshl_add_u64 v[176:177], v[176:177], 2, s[14:15]
	s_waitcnt lgkmcnt(0)
	v_add_f32_e32 v153, v153, v178
	flat_atomic_add_f32 v[176:177], v153
.LBB0_1344:
	s_or_b64 exec, exec, s[18:19]
	v_add_u32_e32 v192, 0xb0, v152
	v_ashrrev_i32_e32 v193, 31, v192
	v_lshlrev_b64 v[152:153], 13, v[192:193]
	v_lshl_add_u64 v[152:153], s[54:55], 0, v[152:153]
	v_lshl_add_u64 v[152:153], v[142:143], 2, v[152:153]
	s_waitcnt lgkmcnt(0)
	s_waitcnt vmcnt(2)
	v_mov_b32_e32 v184, v242
	v_mov_b32_e32 v185, v243
	v_mov_b32_e32 v186, v244
	v_mov_b32_e32 v187, v245
	v_mov_b32_e32 v176, v238
	v_mov_b32_e32 v177, v239
	v_mov_b32_e32 v178, v240
	v_mov_b32_e32 v179, v241
	v_pk_add_f32 v[180:181], v[8:9], v[184:185]
	v_pk_add_f32 v[178:179], v[14:15], v[178:179]
	v_pk_add_f32 v[182:183], v[12:13], v[176:177]
	v_mul_f32_e32 v9, v179, v179
	v_mul_f32_e32 v8, v183, v183
	v_fmac_f32_e32 v8, v182, v182
	v_fmac_f32_e32 v9, v178, v178
	v_add_f32_e32 v8, v8, v9
	v_mul_f32_e32 v9, v181, v181
	v_pk_add_f32 v[176:177], v[10:11], v[186:187]
	v_fmac_f32_e32 v9, v180, v180
	v_add_f32_e32 v8, v8, v9
	v_mul_f32_e32 v9, v177, v177
	v_fmac_f32_e32 v9, v176, v176
	v_add_f32_e32 v196, v9, v8
	s_waitcnt vmcnt(0)
	v_mov_b32_e32 v8, v210
	v_mov_b32_e32 v9, v211
	v_mov_b32_e32 v10, v212
	v_mov_b32_e32 v11, v213
	v_mov_b32_e32 v12, v206
	v_mov_b32_e32 v13, v207
	v_mov_b32_e32 v14, v208
	v_mov_b32_e32 v15, v209
	v_pk_add_f32 v[190:191], v[0:1], v[8:9]
	v_pk_add_f32 v[184:185], v[6:7], v[14:15]
	v_pk_add_f32 v[186:187], v[4:5], v[12:13]
	v_mul_f32_e32 v1, v185, v185
	v_mul_f32_e32 v0, v187, v187
	v_fmac_f32_e32 v0, v186, v186
	v_fmac_f32_e32 v1, v184, v184
	v_add_f32_e32 v0, v0, v1
	v_mul_f32_e32 v1, v191, v191
	v_pk_add_f32 v[188:189], v[2:3], v[10:11]
	v_fmac_f32_e32 v1, v190, v190
	v_add_f32_e32 v0, v0, v1
	v_mul_f32_e32 v1, v189, v189
	v_fmac_f32_e32 v1, v188, v188
	v_add_f32_e32 v0, v1, v0
	v_add_f32_e32 v0, v196, v0
	ds_bpermute_b32 v1, v202, v0
	s_waitcnt lgkmcnt(0)
	v_add_f32_e32 v0, v0, v1
	ds_bpermute_b32 v1, v203, v0
	s_and_saveexec_b64 s[18:19], s[0:1]
	s_cbranch_execz .LBB0_1346
	v_lshl_add_u64 v[2:3], v[192:193], 2, s[14:15]
	s_waitcnt lgkmcnt(0)
	v_add_f32_e32 v0, v0, v1
	flat_atomic_add_f32 v[2:3], v0
